# phase 2: prompt scans assigned statically to the workgroups of XCDs 0-3 (attention starts concentrated on XCDs 4-7 for L2 sharing), queue counter starts at 128
# baseline (speedup 1.0000x reference)
; DI void phase0(const Params& p, char* smem, const int g_wave) {
;     ...
;   if (blockIdx.x == 0 && tid == 0) { ((int*)(p.ws + WS_CTR))[0] = 0; }
; __global__ void __launch_bounds__(512) mega(Params p) {
;   extern __shared__ __attribute__((aligned(16))) char smem[];
;   cg::grid_group grid = cg::this_grid();
;   const int lo = (int)p.ph_lo, hi = (int)p.ph_hi;
;   const int g_wave = __builtin_amdgcn_readfirstlane(threadIdx.x >> 6);
;   if (lo <= 0 && hi > 0) { phase0(p, smem, g_wave); if (hi > 1) grid.sync(); }
_Z4mega6Params:
	s_load_dwordx16 s[12:27], s[0:1], 0x0
	s_load_dwordx16 s[36:51], s[0:1], 0x40
	s_load_dwordx16 s[52:67], s[0:1], 0x80
	s_load_dwordx8 s[68:75], s[0:1], 0xc0
	v_writelane_b32 v255, s2, 0
	v_and_b32_e32 v218, 0x3ff, v0
	v_mbcnt_lo_u32_b32 v1, -1, 0
	v_writelane_b32 v255, s3, 1
	s_add_u32 s2, s0, 0xe8
	s_load_dwordx2 s[84:85], s[0:1], 0xe0
	s_nop 0
	s_load_dword s0, s[0:1], 0xe8
	s_addc_u32 s3, s1, 0
	v_writelane_b32 v255, s2, 2
	s_waitcnt lgkmcnt(0)
	s_cmp_lt_i32 s74, 1
	v_readfirstlane_b32 s75, v218
	v_writelane_b32 v255, s3, 3
	v_writelane_b32 v255, s0, 4
	s_nop 1
	v_writelane_b32 v255, s1, 5
	s_cselect_b64 s[0:1], -1, 0
	s_cmp_gt_i32 s84, 0
	s_cselect_b64 s[2:3], -1, 0
	s_and_b64 s[0:1], s[0:1], s[2:3]
	s_andn2_b64 vcc, exec, s[0:1]
	s_mov_b32 s0, s84
	v_writelane_b32 v255, s0, 6
	s_nop 1
	v_writelane_b32 v255, s1, 7
	s_cbranch_vccnz .LBB0_69
	s_and_b32 s0, s75, 0xffffffc0
	v_mbcnt_hi_u32_b32 v33, -1, v1
	v_or_b32_e32 v32, s0, v33
	v_mov_b32_e32 v4, v32
	v_readlane_b32 s0, v255, 0
	v_readlane_b32 s1, v255, 1
	s_nop 0
	v_or_b32_e32 v2, s0, v4
	v_cmp_eq_u32_e32 vcc, 0, v2
	s_and_saveexec_b64 s[0:1], vcc
	s_cbranch_execz .LBB0_3
	v_mov_b32_e32 v2, 0
	v_mov_b32_e32 v250, 0x80
	global_store_dword v2, v250, s[72:73]

; #define LAUNDER_TID(t) int t = (g_wave << 6) | (int)__builtin_amdgcn_mbcnt_hi(~0u, __builtin_amdgcn_mbcnt_lo(~0u, 0u)); asm volatile("" : "+v"(t))
; DI float wave_sum(float v) { for (int o = 32; o > 0; o >>= 1) v += __shfl_xor(v, o); return v; }
; DI void phase2(const Params& p, char* smem, const int g_wave) {
;   __shared__ int s_item;
;   __shared__ float s_lam;
;   const int wid = g_wave;
;   float lam;
;   {
;     const int lane = (int)__builtin_amdgcn_mbcnt_hi(~0u, __builtin_amdgcn_mbcnt_lo(~0u, 0u));
;     float a = p.lq1[lane] * p.lk1[lane], b = p.lq2[lane] * p.lk2[lane];
;     a = wave_sum(a); b = wave_sum(b);
;     lam = __expf(a) - __expf(b) + 0.2f;
;     if (lane == 0 && g_wave == 0) s_lam = lam;
;   }
;   int* ctr = (int*)(p.ws + WS_CTR);
;   constexpr int N0 = 128, N1 = N0 + 2048, N2 = N1 + 128, N3 = N2 + 64;
;   for (;;) {
;     { LAUNDER_TID(tq); if (tq == 0) s_item = atomicAdd(ctr, 1); }
;     __syncthreads();
;     const int it = __builtin_amdgcn_readfirstlane(s_item);
.LBB0_679:
	s_or_b64 exec, exec, s[0:1]
	s_and_b32 s0, s75, 0xffffffc0
	s_cmpk_lt_u32 s75, 0x80
	s_cselect_b32 s2, 17, 0
	s_lshr_b32 s28, s75, 7
	s_add_i32 s28, s28, 1
	s_cmpk_gt_u32 s75, 0xff
	s_cselect_b64 s[8:9], -1, 0
	s_lshl_b32 s29, s3, 3
	v_or_b32_e32 v196, s0, v2
	s_movk_i32 s6, 0x80
	v_cmp_gt_u32_e64 s[10:11], s6, v196
	s_and_saveexec_b64 s[4:5], s[10:11]
	v_lshlrev_b32_e32 v6, 2, v196
	global_load_dword v7, v6, s[44:45]
	v_add_u32_e32 v6, 0x25100, v6
	s_waitcnt vmcnt(0)
	ds_write_b32 v6, v7
	s_or_b64 exec, exec, s[4:5]
	s_sub_i32 s30, s29, 32
	s_lshl_b32 s0, s3, 4
	s_add_u32 s33, s72, 0x9641000
	s_addc_u32 s75, s73, 0
	v_writelane_b32 v255, s0, 9
	s_add_u32 s0, s72, 0x19741000
	v_writelane_b32 v255, s0, 17
	s_addc_u32 s0, s73, 0
	v_writelane_b32 v255, s0, 19
	s_add_u32 s0, s72, 0x11741000
	v_writelane_b32 v255, s0, 21
	s_addc_u32 s0, s73, 0
	v_writelane_b32 v255, s0, 23
	s_add_u32 s0, s72, 0x22841000
	v_writelane_b32 v255, s0, 10
	s_addc_u32 s0, s73, 0
	v_writelane_b32 v255, s0, 15
	s_add_u32 s0, s72, 0x1a841000
	v_writelane_b32 v255, s0, 11
	s_addc_u32 s0, s73, 0
	s_add_u32 s10, s72, 0x23941000
	s_addc_u32 s11, s73, 0
	v_writelane_b32 v255, s0, 13
	s_add_u32 s0, s70, 0x8100000
	s_addc_u32 s95, s71, 0
	s_add_u32 s16, s72, 0x239a3700
	s_addc_u32 s17, s73, 0
	s_add_u32 s18, s72, 0x239a5000
	v_writelane_b32 v255, s0, 12
	s_addc_u32 s19, s73, 0
	s_lshl_b32 s0, s3, 6
	s_add_i32 s96, s0, 16
	s_add_i32 s96, s96, 0xa100
	v_mov_b32_e32 v3, 0
	s_mov_b64 s[24:25], 0x80
	s_mov_b64 s[26:27], 0x20000
	s_mov_b32 s97, 0x3e38aa3b
	s_mov_b32 s3, 1.0
	s_mov_b32 s98, 0x800000
	s_add_i32 s99, 16, 0x1e700
	s_add_i32 s36, 16, 0x1f800
	s_movk_i32 s37, 0x90
	s_add_i32 s31, 16, 0x1ec00
	s_movk_i32 s86, 0x1900
	s_movk_i32 s87, 0x1000
	s_add_i32 s88, 16, 0x1c300
	s_movk_i32 s89, 0x7fff
	s_mov_b32 s90, 0x7060302
	s_add_i32 s91, 16, 0x1d500
	v_mov_b32_e32 v197, 0x3a27c5ac
	s_add_i32 s92, 16, 0x1a180
	s_add_i32 s93, 16, 0x18180
	s_add_i32 s94, 16, 0x100
	v_mov_b32_e32 v183, 1.0
	v_readlane_b32 s6, v255, 0
	s_nop 3
	s_and_b32 s4, s6, 4
	s_cmp_eq_u32 s4, 0
	s_cbranch_scc0 .LBB0_683
	s_and_b32 s4, s6, 3
	s_lshl_b32 s4, s4, 5
	s_lshr_b32 s6, s6, 3
	s_add_i32 s6, s6, s4
	v_mov_b32_e32 v2, v196
	s_mov_b64 s[0:1], -1
	s_branch .Lq_static

; DI void phase2(const Params& p, char* smem, const int g_wave) {
;     ...
;     const int it = __builtin_amdgcn_readfirstlane(s_item);
;     __syncthreads();
;     if (it >= N3) break;
;     const bool is_scan = it < N0 || (it >= N1 && it < N2);
;     if (is_scan) {
;     ...
;       const bool prm = it < N0; const int c = prm ? it : it - N1;
;       scan_item(p, smem, c >> 4, c & 15, prm, g_wave);
;     ...
;     } else {
;     ...
;       const bool prm = it < N1;
;       int qb, bh;
;       if (prm) { int a = it - N0; qb = 31 - (a >> 6); bh = a & 63; } else { qb = 0; bh = it - N2; }
.Lq_static:
	s_cmpk_gt_i32 s6, 0x93f
	s_cbranch_scc1 .LBB0_682
	s_cmpk_lt_i32 s6, 0x80
	s_cselect_b64 s[38:39], -1, 0
	s_cmpk_gt_i32 s6, 0x7f
	s_cselect_b64 s[40:41], -1, 0
	s_and_b32 s0, s6, 0x7fffff80
	s_cmpk_lg_i32 s0, 0x880
	s_cselect_b64 s[0:1], -1, 0
	s_and_b64 s[4:5], s[40:41], s[0:1]
	s_mov_b64 s[0:1], -1
	s_and_b64 vcc, exec, s[4:5]
	s_cbranch_vccz .LBB0_721
	s_cmpk_lt_u32 s6, 0x880
	s_cselect_b64 s[54:55], -1, 0
	s_cmpk_gt_u32 s6, 0x87f
	s_cselect_b64 s[0:1], -1, 0
	s_mov_b64 s[4:5], -1
	s_and_b64 vcc, exec, s[0:1]
	s_cbranch_vccz .LBB0_691
	s_add_i32 s50, s6, 0xfffff700
	s_mov_b32 s78, 0
	s_cbranch_execnz .LBB0_693
	s_branch .LBB0_692
